# in-place residual GEMM epilogue of the three out-projection phases re-emitted in 4 batches (gates loaded once, 8 source quads per wait) instead of 16 serialized load-wait-store round trips
# speedup vs baseline: 1.0051x; 1.0051x over previous
;     __device__ __forceinline__ void operator()(const f32x4 (&acc)[2][2][4][2], const Unit& u, int wr, int wc, int fr, int fq) const {
;     ...
;         for (int ai = 0; ai < 2; ++ai)
; #pragma unroll
;             for (int m = 0; m < 4; ++m)
; #pragma unroll
;                 for (int bj = 0; bj < 2; ++bj) f(u, ai * 128 + wr * 64 + m * 16 + fr, bj * 128 + wc * 32 + 8 * fq, acc[ai][bj][m][0], acc[ai][bj][m][1]);
;     __device__ __forceinline__ void operator()(const pg8::Unit& u, int rl, int cl, f32x4 v0, f32x4 v1) const {
;         const int b = u.pm / 17, j = u.pm - 17 * b, col = u.pn * 256 + cl;
;         const float* src; float* dst; const float* gate;
;         if (j == 0) { const size_t off = (size_t)(b * CTXL + rl) * D + col; src = co + off; dst = cn + off; gate = modl + 4 * 3072 + 2048 + col; }
;         else { const size_t off = (size_t)(b * SEQ + (j - 1) * 256 + rl) * D + col; src = xo + off; dst = xn + off; gate = modl + b * 3072 + 2048 + col; }
;         const f32x4 a0 = *(const f32x4*)src, a1 = *(const f32x4*)(src + 4), g0 = *(const f32x4*)gate, g1 = *(const f32x4*)(gate + 4);
;         *(f32x4*)dst = a0 + g0 * v0; *(f32x4*)(dst + 4) = a1 + g1 * v1;
;     }
.LBB0_1269:
	s_mul_hi_i32 s17, s42, 0x78787879
	s_lshr_b32 s19, s17, 31
	s_ashr_i32 s17, s17, 3
	s_add_i32 s19, s17, s19
	s_mul_i32 s17, s19, 0xffffffef
	s_add_i32 s42, s17, s42
	v_lshl_or_b32 v148, s44, 8, v159
	s_lshl_b32 s17, s19, 12
	s_lshl_b32 s44, s42, 8
	s_mul_i32 s46, s19, 0xc00
	s_add_i32 s17, s17, s44
	s_ashr_i32 s47, s46, 31
	s_addk_i32 s17, 0xff00
	s_lshl_b32 s19, s19, 8
	s_lshl_b64 s[46:47], s[46:47], 2
	s_add_u32 s44, s26, s46
	s_addc_u32 s46, s27, s47
	s_add_u32 s44, s44, 0x11000
	s_addc_u32 s48, s46, 0
	v_add_u32_e32 v150, s17, v133
	v_add_u32_e32 v164, s19, v133
	s_cmp_eq_u32 s42, 0
	v_ashrrev_i32_e32 v151, 31, v150
	v_ashrrev_i32_e32 v165, 31, v164
	v_lshlrev_b64 v[164:165], 12, v[164:165]
	v_lshlrev_b64 v[150:151], 12, v[150:151]
	s_cselect_b64 vcc, -1, 0
	v_ashrrev_i32_e32 v149, 31, v148
	v_lshl_add_u64 v[164:165], s[8:9], 0, v[164:165]
	v_lshl_add_u64 v[150:151], s[12:13], 0, v[150:151]
	s_and_b64 s[46:47], vcc, exec
	v_cndmask_b32_e32 v165, v151, v165, vcc
	s_cselect_b32 s47, s63, s48
	s_cselect_b32 s46, s62, s44
	v_cndmask_b32_e32 v164, v150, v164, vcc
	v_lshlrev_b64 v[150:151], 2, v[148:149]
	v_lshl_add_u64 v[148:149], s[46:47], 0, v[150:151]
	v_lshl_add_u64 v[180:181], v[164:165], 0, v[150:151]
	global_load_dwordx4 v[164:167], v[148:149], off
	global_load_dwordx4 v[168:171], v[148:149], off offset:16
	global_load_dwordx4 v[176:179], v[148:149], off offset:512
	global_load_dwordx4 v[182:185], v[148:149], off offset:528
	v_add_u32_e32 v220, s19, v152
	v_add_u32_e32 v222, s17, v152
	v_ashrrev_i32_e32 v221, 31, v220
	v_ashrrev_i32_e32 v223, 31, v222
	v_lshlrev_b64 v[220:221], 12, v[220:221]
	v_lshlrev_b64 v[222:223], 12, v[222:223]
	v_lshl_add_u64 v[220:221], s[8:9], 0, v[220:221]
	v_lshl_add_u64 v[222:223], s[12:13], 0, v[222:223]
	v_cndmask_b32_e32 v221, v223, v221, vcc
	v_cndmask_b32_e32 v220, v222, v220, vcc
	v_lshl_add_u64 v[220:221], v[220:221], 0, v[150:151]
	global_load_dwordx4 v[186:189], v[180:181], off
	global_load_dwordx4 v[190:193], v[180:181], off offset:16
	global_load_dwordx4 v[194:197], v[180:181], off offset:512
	global_load_dwordx4 v[198:201], v[180:181], off offset:528
	global_load_dwordx4 v[202:205], v[220:221], off
	global_load_dwordx4 v[206:209], v[220:221], off offset:16
	global_load_dwordx4 v[210:213], v[220:221], off offset:512
	global_load_dwordx4 v[214:217], v[220:221], off offset:528
	s_waitcnt vmcnt(0)
	v_pk_fma_f32 v[186:187], v[124:125], v[164:165], v[186:187]
	v_pk_fma_f32 v[188:189], v[126:127], v[166:167], v[188:189]
	v_pk_fma_f32 v[190:191], v[120:121], v[168:169], v[190:191]
	v_pk_fma_f32 v[192:193], v[122:123], v[170:171], v[192:193]
	v_pk_fma_f32 v[194:195], v[112:113], v[176:177], v[194:195]
	v_pk_fma_f32 v[196:197], v[114:115], v[178:179], v[196:197]
	v_pk_fma_f32 v[198:199], v[108:109], v[182:183], v[198:199]
	v_pk_fma_f32 v[200:201], v[110:111], v[184:185], v[200:201]
	v_pk_fma_f32 v[202:203], v[116:117], v[164:165], v[202:203]
	v_pk_fma_f32 v[204:205], v[118:119], v[166:167], v[204:205]
	v_pk_fma_f32 v[206:207], v[104:105], v[168:169], v[206:207]
	v_pk_fma_f32 v[208:209], v[106:107], v[170:171], v[208:209]
	v_pk_fma_f32 v[210:211], v[96:97], v[176:177], v[210:211]
	v_pk_fma_f32 v[212:213], v[98:99], v[178:179], v[212:213]
	v_pk_fma_f32 v[214:215], v[92:93], v[182:183], v[214:215]
	v_pk_fma_f32 v[216:217], v[94:95], v[184:185], v[216:217]
	global_store_dwordx4 v[180:181], v[186:189], off
	global_store_dwordx4 v[180:181], v[190:193], off offset:16
	global_store_dwordx4 v[180:181], v[194:197], off offset:512
	global_store_dwordx4 v[180:181], v[198:201], off offset:528
	global_store_dwordx4 v[220:221], v[202:205], off
	global_store_dwordx4 v[220:221], v[206:209], off offset:16
	global_store_dwordx4 v[220:221], v[210:213], off offset:512
	global_store_dwordx4 v[220:221], v[214:217], off offset:528
	s_nop 1
	v_add_u32_e32 v218, s19, v153
	v_add_u32_e32 v222, s17, v153
	v_ashrrev_i32_e32 v219, 31, v218
	v_ashrrev_i32_e32 v223, 31, v222
	v_lshlrev_b64 v[218:219], 12, v[218:219]
	v_lshlrev_b64 v[222:223], 12, v[222:223]
	v_lshl_add_u64 v[218:219], s[8:9], 0, v[218:219]
	v_lshl_add_u64 v[222:223], s[12:13], 0, v[222:223]
	v_cndmask_b32_e32 v219, v223, v219, vcc
	v_cndmask_b32_e32 v218, v222, v218, vcc
	v_lshl_add_u64 v[218:219], v[218:219], 0, v[150:151]
	v_add_u32_e32 v220, s19, v154
	v_add_u32_e32 v222, s17, v154
	v_ashrrev_i32_e32 v221, 31, v220
	v_ashrrev_i32_e32 v223, 31, v222
	v_lshlrev_b64 v[220:221], 12, v[220:221]
	v_lshlrev_b64 v[222:223], 12, v[222:223]
	v_lshl_add_u64 v[220:221], s[8:9], 0, v[220:221]
	v_lshl_add_u64 v[222:223], s[12:13], 0, v[222:223]
	v_cndmask_b32_e32 v221, v223, v221, vcc
	v_cndmask_b32_e32 v220, v222, v220, vcc
	v_lshl_add_u64 v[220:221], v[220:221], 0, v[150:151]
	global_load_dwordx4 v[186:189], v[218:219], off
	global_load_dwordx4 v[190:193], v[218:219], off offset:16
	global_load_dwordx4 v[194:197], v[218:219], off offset:512
	global_load_dwordx4 v[198:201], v[218:219], off offset:528
	global_load_dwordx4 v[202:205], v[220:221], off
	global_load_dwordx4 v[206:209], v[220:221], off offset:16
	global_load_dwordx4 v[210:213], v[220:221], off offset:512
	global_load_dwordx4 v[214:217], v[220:221], off offset:528
	s_waitcnt vmcnt(0)
;     __device__ __forceinline__ void operator()(const pg8::Unit& u, int rl, int cl, f32x4 v0, f32x4 v1) const {
;         const int b = u.pm / 17, j = u.pm - 17 * b, col = u.pn * 256 + cl;
;         const float* src; float* dst; const float* gate;
;         if (j == 0) { const size_t off = (size_t)(b * CTXL + rl) * D + col; src = co + off; dst = cn + off; gate = modl + 4 * 3072 + 2048 + col; }
;         else { const size_t off = (size_t)(b * SEQ + (j - 1) * 256 + rl) * D + col; src = xo + off; dst = xn + off; gate = modl + b * 3072 + 2048 + col; }
;         const f32x4 a0 = *(const f32x4*)src, a1 = *(const f32x4*)(src + 4), g0 = *(const f32x4*)gate, g1 = *(const f32x4*)(gate + 4);
;         *(f32x4*)dst = a0 + g0 * v0; *(f32x4*)(dst + 4) = a1 + g1 * v1;
	v_pk_fma_f32 v[186:187], v[100:101], v[164:165], v[186:187]
	v_pk_fma_f32 v[188:189], v[102:103], v[166:167], v[188:189]
	v_pk_fma_f32 v[190:191], v[88:89], v[168:169], v[190:191]
	v_pk_fma_f32 v[192:193], v[90:91], v[170:171], v[192:193]
	v_pk_fma_f32 v[194:195], v[80:81], v[176:177], v[194:195]
	v_pk_fma_f32 v[196:197], v[82:83], v[178:179], v[196:197]
	v_pk_fma_f32 v[198:199], v[76:77], v[182:183], v[198:199]
	v_pk_fma_f32 v[200:201], v[78:79], v[184:185], v[200:201]
	v_pk_fma_f32 v[202:203], v[84:85], v[164:165], v[202:203]
	v_pk_fma_f32 v[204:205], v[86:87], v[166:167], v[204:205]
	v_pk_fma_f32 v[206:207], v[72:73], v[168:169], v[206:207]
	v_pk_fma_f32 v[208:209], v[74:75], v[170:171], v[208:209]
	v_pk_fma_f32 v[210:211], v[68:69], v[176:177], v[210:211]
	v_pk_fma_f32 v[212:213], v[70:71], v[178:179], v[212:213]
	v_pk_fma_f32 v[214:215], v[64:65], v[182:183], v[214:215]
	v_pk_fma_f32 v[216:217], v[66:67], v[184:185], v[216:217]
	global_store_dwordx4 v[218:219], v[186:189], off
	global_store_dwordx4 v[218:219], v[190:193], off offset:16
	global_store_dwordx4 v[218:219], v[194:197], off offset:512
	global_store_dwordx4 v[218:219], v[198:201], off offset:528
	global_store_dwordx4 v[220:221], v[202:205], off
	global_store_dwordx4 v[220:221], v[206:209], off offset:16
	global_store_dwordx4 v[220:221], v[210:213], off offset:512
	global_store_dwordx4 v[220:221], v[214:217], off offset:528
	s_nop 1
	v_add_u32_e32 v218, s19, v155
	v_add_u32_e32 v222, s17, v155
	v_ashrrev_i32_e32 v219, 31, v218
	v_ashrrev_i32_e32 v223, 31, v222
	v_lshlrev_b64 v[218:219], 12, v[218:219]
	v_lshlrev_b64 v[222:223], 12, v[222:223]
	v_lshl_add_u64 v[218:219], s[8:9], 0, v[218:219]
	v_lshl_add_u64 v[222:223], s[12:13], 0, v[222:223]
	v_cndmask_b32_e32 v219, v223, v219, vcc
	v_cndmask_b32_e32 v218, v222, v218, vcc
	v_lshl_add_u64 v[218:219], v[218:219], 0, v[150:151]
	v_add_u32_e32 v220, s19, v156
	v_add_u32_e32 v222, s17, v156
	v_ashrrev_i32_e32 v221, 31, v220
	v_ashrrev_i32_e32 v223, 31, v222
	v_lshlrev_b64 v[220:221], 12, v[220:221]
	v_lshlrev_b64 v[222:223], 12, v[222:223]
	v_lshl_add_u64 v[220:221], s[8:9], 0, v[220:221]
	v_lshl_add_u64 v[222:223], s[12:13], 0, v[222:223]
	v_cndmask_b32_e32 v221, v223, v221, vcc
	v_cndmask_b32_e32 v220, v222, v220, vcc
	v_lshl_add_u64 v[220:221], v[220:221], 0, v[150:151]
	global_load_dwordx4 v[186:189], v[218:219], off
	global_load_dwordx4 v[190:193], v[218:219], off offset:16
	global_load_dwordx4 v[194:197], v[218:219], off offset:512
	global_load_dwordx4 v[198:201], v[218:219], off offset:528
	global_load_dwordx4 v[202:205], v[220:221], off
	global_load_dwordx4 v[206:209], v[220:221], off offset:16
	global_load_dwordx4 v[210:213], v[220:221], off offset:512
	global_load_dwordx4 v[214:217], v[220:221], off offset:528
	s_waitcnt vmcnt(0)
; #define PG8_BAR __builtin_amdgcn_s_barrier()
; template <class Epi, class Sched, bool ALIGN_EPI = false, bool SP2 = false>
; __device__ __forceinline__ void gemm_phase(PG8_LAS unsigned char* lds, const Gemm g, const Sched& S, const Epi& E) {
;     ...
;         if constexpr (ALIGN_EPI) { if (wr == 0) PG8_BAR; }
;         if constexpr (!Epi::AFTER_DRAIN) { E(acc, cur, wr, wc, fr, fq); S.done(cur); }
;         if (!has_next) break;
; #pragma unroll
;         for (int a = 0; a < 2; ++a)
; #pragma unroll
;             for (int b = 0; b < 2; ++b)
; #pragma unroll
;                 for (int m = 0; m < 4; ++m)
; #pragma unroll
;                     for (int n = 0; n < 2; ++n) acc[a][b][m][n] = (f32x4){0.f, 0.f, 0.f, 0.f};
;         cur = nxt; cA = nA; cB = nB; ++ui;
;         if constexpr (ALIGN_EPI) { if (wr == 1) PG8_BAR; }
;     __device__ __forceinline__ void operator()(const pg8::Unit& u, int rl, int cl, f32x4 v0, f32x4 v1) const {
;         const int b = u.pm / 17, j = u.pm - 17 * b, col = u.pn * 256 + cl;
;         const float* src; float* dst; const float* gate;
;         if (j == 0) { const size_t off = (size_t)(b * CTXL + rl) * D + col; src = co + off; dst = cn + off; gate = modl + 4 * 3072 + 2048 + col; }
;         else { const size_t off = (size_t)(b * SEQ + (j - 1) * 256 + rl) * D + col; src = xo + off; dst = xn + off; gate = modl + b * 3072 + 2048 + col; }
;         const f32x4 a0 = *(const f32x4*)src, a1 = *(const f32x4*)(src + 4), g0 = *(const f32x4*)gate, g1 = *(const f32x4*)(gate + 4);
;         *(f32x4*)dst = a0 + g0 * v0; *(f32x4*)(dst + 4) = a1 + g1 * v1;
	v_pk_fma_f32 v[186:187], v[60:61], v[164:165], v[186:187]
	v_pk_fma_f32 v[188:189], v[62:63], v[166:167], v[188:189]
	v_pk_fma_f32 v[190:191], v[56:57], v[168:169], v[190:191]
	v_pk_fma_f32 v[192:193], v[58:59], v[170:171], v[192:193]
	v_pk_fma_f32 v[194:195], v[48:49], v[176:177], v[194:195]
	v_pk_fma_f32 v[196:197], v[50:51], v[178:179], v[196:197]
	v_pk_fma_f32 v[198:199], v[44:45], v[182:183], v[198:199]
	v_pk_fma_f32 v[200:201], v[46:47], v[184:185], v[200:201]
	v_pk_fma_f32 v[202:203], v[52:53], v[164:165], v[202:203]
	v_pk_fma_f32 v[204:205], v[54:55], v[166:167], v[204:205]
	v_pk_fma_f32 v[206:207], v[40:41], v[168:169], v[206:207]
	v_pk_fma_f32 v[208:209], v[42:43], v[170:171], v[208:209]
	v_pk_fma_f32 v[210:211], v[32:33], v[176:177], v[210:211]
	v_pk_fma_f32 v[212:213], v[34:35], v[178:179], v[212:213]
	v_pk_fma_f32 v[214:215], v[28:29], v[182:183], v[214:215]
	v_pk_fma_f32 v[216:217], v[30:31], v[184:185], v[216:217]
	global_store_dwordx4 v[218:219], v[186:189], off
	global_store_dwordx4 v[218:219], v[190:193], off offset:16
	global_store_dwordx4 v[218:219], v[194:197], off offset:512
	global_store_dwordx4 v[218:219], v[198:201], off offset:528
	global_store_dwordx4 v[220:221], v[202:205], off
	global_store_dwordx4 v[220:221], v[206:209], off offset:16
	global_store_dwordx4 v[220:221], v[210:213], off offset:512
	global_store_dwordx4 v[220:221], v[214:217], off offset:528
	s_nop 1
	v_add_u32_e32 v218, s19, v157
	v_add_u32_e32 v222, s17, v157
	v_ashrrev_i32_e32 v219, 31, v218
	v_ashrrev_i32_e32 v223, 31, v222
	v_lshlrev_b64 v[218:219], 12, v[218:219]
	v_lshlrev_b64 v[222:223], 12, v[222:223]
	v_lshl_add_u64 v[218:219], s[8:9], 0, v[218:219]
	v_lshl_add_u64 v[222:223], s[12:13], 0, v[222:223]
	v_cndmask_b32_e32 v219, v223, v219, vcc
	v_cndmask_b32_e32 v218, v222, v218, vcc
	v_lshl_add_u64 v[218:219], v[218:219], 0, v[150:151]
	v_add_u32_e32 v220, s19, v158
	v_add_u32_e32 v222, s17, v158
	v_ashrrev_i32_e32 v221, 31, v220
	v_ashrrev_i32_e32 v223, 31, v222
	v_lshlrev_b64 v[220:221], 12, v[220:221]
	v_lshlrev_b64 v[222:223], 12, v[222:223]
	v_lshl_add_u64 v[220:221], s[8:9], 0, v[220:221]
	v_lshl_add_u64 v[222:223], s[12:13], 0, v[222:223]
	v_cndmask_b32_e32 v221, v223, v221, vcc
	v_cndmask_b32_e32 v220, v222, v220, vcc
	v_lshl_add_u64 v[220:221], v[220:221], 0, v[150:151]
	global_load_dwordx4 v[186:189], v[218:219], off
	global_load_dwordx4 v[190:193], v[218:219], off offset:16
	global_load_dwordx4 v[194:197], v[218:219], off offset:512
	global_load_dwordx4 v[198:201], v[218:219], off offset:528
	global_load_dwordx4 v[202:205], v[220:221], off
	global_load_dwordx4 v[206:209], v[220:221], off offset:16
	global_load_dwordx4 v[210:213], v[220:221], off offset:512
	global_load_dwordx4 v[214:217], v[220:221], off offset:528
	s_waitcnt vmcnt(0)
	v_pk_fma_f32 v[186:187], v[36:37], v[164:165], v[186:187]
	v_pk_fma_f32 v[188:189], v[38:39], v[166:167], v[188:189]
	v_pk_fma_f32 v[190:191], v[24:25], v[168:169], v[190:191]
	v_pk_fma_f32 v[192:193], v[26:27], v[170:171], v[192:193]
	v_pk_fma_f32 v[194:195], v[16:17], v[176:177], v[194:195]
	v_pk_fma_f32 v[196:197], v[18:19], v[178:179], v[196:197]
	v_pk_fma_f32 v[198:199], v[12:13], v[182:183], v[198:199]
	v_pk_fma_f32 v[200:201], v[14:15], v[184:185], v[200:201]
	v_pk_fma_f32 v[202:203], v[20:21], v[164:165], v[202:203]
	v_pk_fma_f32 v[204:205], v[22:23], v[166:167], v[204:205]
	v_pk_fma_f32 v[206:207], v[8:9], v[168:169], v[206:207]
	v_pk_fma_f32 v[208:209], v[10:11], v[170:171], v[208:209]
	v_pk_fma_f32 v[210:211], v[4:5], v[176:177], v[210:211]
	v_pk_fma_f32 v[212:213], v[6:7], v[178:179], v[212:213]
	v_pk_fma_f32 v[214:215], v[0:1], v[182:183], v[214:215]
	v_pk_fma_f32 v[216:217], v[2:3], v[184:185], v[216:217]
	global_store_dwordx4 v[218:219], v[186:189], off
	global_store_dwordx4 v[218:219], v[190:193], off offset:16
	global_store_dwordx4 v[218:219], v[194:197], off offset:512
	global_store_dwordx4 v[218:219], v[198:201], off offset:528
	global_store_dwordx4 v[220:221], v[202:205], off
	global_store_dwordx4 v[220:221], v[206:209], off offset:16
	global_store_dwordx4 v[220:221], v[210:213], off offset:512
	global_store_dwordx4 v[220:221], v[214:217], off offset:528
	s_nop 1
	s_andn2_b64 vcc, exec, s[22:23]
	s_mov_b64 s[22:23], -1
	s_cbranch_vccnz .LBB0_1262
	s_andn2_b64 vcc, exec, s[6:7]
	s_cbranch_vccnz .LBB0_1261
	s_barrier
	s_branch .LBB0_1261

;     __device__ __forceinline__ void operator()(const f32x4 (&acc)[2][2][4][2], const Unit& u, int wr, int wc, int fr, int fq) const {
;     ...
;         for (int ai = 0; ai < 2; ++ai)
; #pragma unroll
;             for (int m = 0; m < 4; ++m)
; #pragma unroll
;                 for (int bj = 0; bj < 2; ++bj) f(u, ai * 128 + wr * 64 + m * 16 + fr, bj * 128 + wc * 32 + 8 * fq, acc[ai][bj][m][0], acc[ai][bj][m][1]);
;     __device__ __forceinline__ void operator()(const pg8::Unit& u, int rl, int cl, f32x4 v0, f32x4 v1) const {
;         const int b = u.pm / 17, j = u.pm - 17 * b, col = u.pn * 256 + cl;
;         const float* src; float* dst; const float* gate;
;         if (j == 0) { const size_t off = (size_t)(b * CTXL + rl) * D + col; src = co + off; dst = cn + off; gate = modl + 4 * 3072 + 2048 + col; }
;         else { const size_t off = (size_t)(b * SEQ + (j - 1) * 256 + rl) * D + col; src = xo + off; dst = xn + off; gate = modl + b * 3072 + 2048 + col; }
;         const f32x4 a0 = *(const f32x4*)src, a1 = *(const f32x4*)(src + 4), g0 = *(const f32x4*)gate, g1 = *(const f32x4*)(gate + 4);
;         *(f32x4*)dst = a0 + g0 * v0; *(f32x4*)(dst + 4) = a1 + g1 * v1;
;     }
.LBB0_1960:
	s_mul_hi_i32 s19, s44, 0x78787879
	s_lshr_b32 s21, s19, 31
	s_ashr_i32 s19, s19, 3
	s_add_i32 s21, s19, s21
	s_mul_i32 s19, s21, 0xffffffef
	s_add_i32 s44, s19, s44
	v_lshl_or_b32 v148, s46, 8, v159
	s_lshl_b32 s19, s21, 12
	s_lshl_b32 s46, s44, 8
	s_mul_i32 s48, s21, 0xc00
	s_add_i32 s19, s19, s46
	s_ashr_i32 s49, s48, 31
	s_addk_i32 s19, 0xff00
	s_lshl_b32 s21, s21, 8
	s_lshl_b64 s[48:49], s[48:49], 2
	s_add_u32 s46, s26, s48
	s_addc_u32 s48, s27, s49
	s_add_u32 s46, s46, 0x20000
	s_addc_u32 s50, s48, 0
	v_add_u32_e32 v150, s19, v133
	v_add_u32_e32 v164, s21, v133
	s_cmp_eq_u32 s44, 0
	v_ashrrev_i32_e32 v151, 31, v150
	v_ashrrev_i32_e32 v165, 31, v164
	v_lshlrev_b64 v[164:165], 12, v[164:165]
	v_lshlrev_b64 v[150:151], 12, v[150:151]
	s_cselect_b64 vcc, -1, 0
	v_ashrrev_i32_e32 v149, 31, v148
	v_lshl_add_u64 v[164:165], s[8:9], 0, v[164:165]
	v_lshl_add_u64 v[150:151], s[14:15], 0, v[150:151]
	s_and_b64 s[48:49], vcc, exec
	v_cndmask_b32_e32 v165, v151, v165, vcc
	s_cselect_b32 s49, s65, s50
	s_cselect_b32 s48, s64, s46
	v_cndmask_b32_e32 v164, v150, v164, vcc
	v_lshlrev_b64 v[150:151], 2, v[148:149]
	v_lshl_add_u64 v[148:149], s[48:49], 0, v[150:151]
	v_lshl_add_u64 v[180:181], v[164:165], 0, v[150:151]
	global_load_dwordx4 v[164:167], v[148:149], off
	global_load_dwordx4 v[168:171], v[148:149], off offset:16
	global_load_dwordx4 v[176:179], v[148:149], off offset:512
	global_load_dwordx4 v[182:185], v[148:149], off offset:528
	v_add_u32_e32 v220, s21, v152
	v_add_u32_e32 v222, s19, v152
	v_ashrrev_i32_e32 v221, 31, v220
	v_ashrrev_i32_e32 v223, 31, v222
	v_lshlrev_b64 v[220:221], 12, v[220:221]
	v_lshlrev_b64 v[222:223], 12, v[222:223]
	v_lshl_add_u64 v[220:221], s[8:9], 0, v[220:221]
	v_lshl_add_u64 v[222:223], s[14:15], 0, v[222:223]
	v_cndmask_b32_e32 v221, v223, v221, vcc
	v_cndmask_b32_e32 v220, v222, v220, vcc
	v_lshl_add_u64 v[220:221], v[220:221], 0, v[150:151]
	global_load_dwordx4 v[186:189], v[180:181], off
	global_load_dwordx4 v[190:193], v[180:181], off offset:16
	global_load_dwordx4 v[194:197], v[180:181], off offset:512
	global_load_dwordx4 v[198:201], v[180:181], off offset:528
	global_load_dwordx4 v[202:205], v[220:221], off
	global_load_dwordx4 v[206:209], v[220:221], off offset:16
	global_load_dwordx4 v[210:213], v[220:221], off offset:512
	global_load_dwordx4 v[214:217], v[220:221], off offset:528
	s_waitcnt vmcnt(0)
	v_pk_fma_f32 v[186:187], v[124:125], v[164:165], v[186:187]
	v_pk_fma_f32 v[188:189], v[126:127], v[166:167], v[188:189]
	v_pk_fma_f32 v[190:191], v[120:121], v[168:169], v[190:191]
	v_pk_fma_f32 v[192:193], v[122:123], v[170:171], v[192:193]
	v_pk_fma_f32 v[194:195], v[112:113], v[176:177], v[194:195]
	v_pk_fma_f32 v[196:197], v[114:115], v[178:179], v[196:197]
	v_pk_fma_f32 v[198:199], v[108:109], v[182:183], v[198:199]
	v_pk_fma_f32 v[200:201], v[110:111], v[184:185], v[200:201]
	v_pk_fma_f32 v[202:203], v[116:117], v[164:165], v[202:203]
	v_pk_fma_f32 v[204:205], v[118:119], v[166:167], v[204:205]
	v_pk_fma_f32 v[206:207], v[104:105], v[168:169], v[206:207]
	v_pk_fma_f32 v[208:209], v[106:107], v[170:171], v[208:209]
	v_pk_fma_f32 v[210:211], v[96:97], v[176:177], v[210:211]
	v_pk_fma_f32 v[212:213], v[98:99], v[178:179], v[212:213]
	v_pk_fma_f32 v[214:215], v[92:93], v[182:183], v[214:215]
	v_pk_fma_f32 v[216:217], v[94:95], v[184:185], v[216:217]
	global_store_dwordx4 v[180:181], v[186:189], off
	global_store_dwordx4 v[180:181], v[190:193], off offset:16
	global_store_dwordx4 v[180:181], v[194:197], off offset:512
	global_store_dwordx4 v[180:181], v[198:201], off offset:528
	global_store_dwordx4 v[220:221], v[202:205], off
	global_store_dwordx4 v[220:221], v[206:209], off offset:16
	global_store_dwordx4 v[220:221], v[210:213], off offset:512
	global_store_dwordx4 v[220:221], v[214:217], off offset:528
	s_nop 1
	v_add_u32_e32 v218, s21, v153
	v_add_u32_e32 v222, s19, v153
	v_ashrrev_i32_e32 v219, 31, v218
	v_ashrrev_i32_e32 v223, 31, v222
	v_lshlrev_b64 v[218:219], 12, v[218:219]
	v_lshlrev_b64 v[222:223], 12, v[222:223]
	v_lshl_add_u64 v[218:219], s[8:9], 0, v[218:219]
	v_lshl_add_u64 v[222:223], s[14:15], 0, v[222:223]
	v_cndmask_b32_e32 v219, v223, v219, vcc
	v_cndmask_b32_e32 v218, v222, v218, vcc
	v_lshl_add_u64 v[218:219], v[218:219], 0, v[150:151]
	v_add_u32_e32 v220, s21, v154
	v_add_u32_e32 v222, s19, v154
	v_ashrrev_i32_e32 v221, 31, v220
	v_ashrrev_i32_e32 v223, 31, v222
	v_lshlrev_b64 v[220:221], 12, v[220:221]
	v_lshlrev_b64 v[222:223], 12, v[222:223]
	v_lshl_add_u64 v[220:221], s[8:9], 0, v[220:221]
	v_lshl_add_u64 v[222:223], s[14:15], 0, v[222:223]
	v_cndmask_b32_e32 v221, v223, v221, vcc
	v_cndmask_b32_e32 v220, v222, v220, vcc
	v_lshl_add_u64 v[220:221], v[220:221], 0, v[150:151]
	global_load_dwordx4 v[186:189], v[218:219], off
	global_load_dwordx4 v[190:193], v[218:219], off offset:16
	global_load_dwordx4 v[194:197], v[218:219], off offset:512
	global_load_dwordx4 v[198:201], v[218:219], off offset:528
	global_load_dwordx4 v[202:205], v[220:221], off
	global_load_dwordx4 v[206:209], v[220:221], off offset:16
	global_load_dwordx4 v[210:213], v[220:221], off offset:512
	global_load_dwordx4 v[214:217], v[220:221], off offset:528
	s_waitcnt vmcnt(0)
;     __device__ __forceinline__ void operator()(const pg8::Unit& u, int rl, int cl, f32x4 v0, f32x4 v1) const {
;         const int b = u.pm / 17, j = u.pm - 17 * b, col = u.pn * 256 + cl;
;         const float* src; float* dst; const float* gate;
;         if (j == 0) { const size_t off = (size_t)(b * CTXL + rl) * D + col; src = co + off; dst = cn + off; gate = modl + 4 * 3072 + 2048 + col; }
;         else { const size_t off = (size_t)(b * SEQ + (j - 1) * 256 + rl) * D + col; src = xo + off; dst = xn + off; gate = modl + b * 3072 + 2048 + col; }
;         const f32x4 a0 = *(const f32x4*)src, a1 = *(const f32x4*)(src + 4), g0 = *(const f32x4*)gate, g1 = *(const f32x4*)(gate + 4);
;         *(f32x4*)dst = a0 + g0 * v0; *(f32x4*)(dst + 4) = a1 + g1 * v1;
	v_pk_fma_f32 v[186:187], v[100:101], v[164:165], v[186:187]
	v_pk_fma_f32 v[188:189], v[102:103], v[166:167], v[188:189]
	v_pk_fma_f32 v[190:191], v[88:89], v[168:169], v[190:191]
	v_pk_fma_f32 v[192:193], v[90:91], v[170:171], v[192:193]
	v_pk_fma_f32 v[194:195], v[80:81], v[176:177], v[194:195]
	v_pk_fma_f32 v[196:197], v[82:83], v[178:179], v[196:197]
	v_pk_fma_f32 v[198:199], v[76:77], v[182:183], v[198:199]
	v_pk_fma_f32 v[200:201], v[78:79], v[184:185], v[200:201]
	v_pk_fma_f32 v[202:203], v[84:85], v[164:165], v[202:203]
	v_pk_fma_f32 v[204:205], v[86:87], v[166:167], v[204:205]
	v_pk_fma_f32 v[206:207], v[72:73], v[168:169], v[206:207]
	v_pk_fma_f32 v[208:209], v[74:75], v[170:171], v[208:209]
	v_pk_fma_f32 v[210:211], v[68:69], v[176:177], v[210:211]
	v_pk_fma_f32 v[212:213], v[70:71], v[178:179], v[212:213]
	v_pk_fma_f32 v[214:215], v[64:65], v[182:183], v[214:215]
	v_pk_fma_f32 v[216:217], v[66:67], v[184:185], v[216:217]
	global_store_dwordx4 v[218:219], v[186:189], off
	global_store_dwordx4 v[218:219], v[190:193], off offset:16
	global_store_dwordx4 v[218:219], v[194:197], off offset:512
	global_store_dwordx4 v[218:219], v[198:201], off offset:528
	global_store_dwordx4 v[220:221], v[202:205], off
	global_store_dwordx4 v[220:221], v[206:209], off offset:16
	global_store_dwordx4 v[220:221], v[210:213], off offset:512
	global_store_dwordx4 v[220:221], v[214:217], off offset:528
	s_nop 1
	v_add_u32_e32 v218, s21, v155
	v_add_u32_e32 v222, s19, v155
	v_ashrrev_i32_e32 v219, 31, v218
	v_ashrrev_i32_e32 v223, 31, v222
	v_lshlrev_b64 v[218:219], 12, v[218:219]
	v_lshlrev_b64 v[222:223], 12, v[222:223]
	v_lshl_add_u64 v[218:219], s[8:9], 0, v[218:219]
	v_lshl_add_u64 v[222:223], s[14:15], 0, v[222:223]
	v_cndmask_b32_e32 v219, v223, v219, vcc
	v_cndmask_b32_e32 v218, v222, v218, vcc
	v_lshl_add_u64 v[218:219], v[218:219], 0, v[150:151]
	v_add_u32_e32 v220, s21, v156
	v_add_u32_e32 v222, s19, v156
	v_ashrrev_i32_e32 v221, 31, v220
	v_ashrrev_i32_e32 v223, 31, v222
	v_lshlrev_b64 v[220:221], 12, v[220:221]
	v_lshlrev_b64 v[222:223], 12, v[222:223]
	v_lshl_add_u64 v[220:221], s[8:9], 0, v[220:221]
	v_lshl_add_u64 v[222:223], s[14:15], 0, v[222:223]
	v_cndmask_b32_e32 v221, v223, v221, vcc
	v_cndmask_b32_e32 v220, v222, v220, vcc
	v_lshl_add_u64 v[220:221], v[220:221], 0, v[150:151]
	global_load_dwordx4 v[186:189], v[218:219], off
	global_load_dwordx4 v[190:193], v[218:219], off offset:16
	global_load_dwordx4 v[194:197], v[218:219], off offset:512
	global_load_dwordx4 v[198:201], v[218:219], off offset:528
	global_load_dwordx4 v[202:205], v[220:221], off
	global_load_dwordx4 v[206:209], v[220:221], off offset:16
	global_load_dwordx4 v[210:213], v[220:221], off offset:512
	global_load_dwordx4 v[214:217], v[220:221], off offset:528
	s_waitcnt vmcnt(0)
; #define PG8_BAR __builtin_amdgcn_s_barrier()
; template <class Epi, class Sched, bool ALIGN_EPI = false, bool SP2 = false>
; __device__ __forceinline__ void gemm_phase(PG8_LAS unsigned char* lds, const Gemm g, const Sched& S, const Epi& E) {
;     ...
;         if constexpr (ALIGN_EPI) { if (wr == 0) PG8_BAR; }
;         if constexpr (!Epi::AFTER_DRAIN) { E(acc, cur, wr, wc, fr, fq); S.done(cur); }
;         if (!has_next) break;
; #pragma unroll
;         for (int a = 0; a < 2; ++a)
; #pragma unroll
;             for (int b = 0; b < 2; ++b)
; #pragma unroll
;                 for (int m = 0; m < 4; ++m)
; #pragma unroll
;                     for (int n = 0; n < 2; ++n) acc[a][b][m][n] = (f32x4){0.f, 0.f, 0.f, 0.f};
;         cur = nxt; cA = nA; cB = nB; ++ui;
;         if constexpr (ALIGN_EPI) { if (wr == 1) PG8_BAR; }
;     __device__ __forceinline__ void operator()(const pg8::Unit& u, int rl, int cl, f32x4 v0, f32x4 v1) const {
;         const int b = u.pm / 17, j = u.pm - 17 * b, col = u.pn * 256 + cl;
;         const float* src; float* dst; const float* gate;
;         if (j == 0) { const size_t off = (size_t)(b * CTXL + rl) * D + col; src = co + off; dst = cn + off; gate = modl + 4 * 3072 + 2048 + col; }
;         else { const size_t off = (size_t)(b * SEQ + (j - 1) * 256 + rl) * D + col; src = xo + off; dst = xn + off; gate = modl + b * 3072 + 2048 + col; }
;         const f32x4 a0 = *(const f32x4*)src, a1 = *(const f32x4*)(src + 4), g0 = *(const f32x4*)gate, g1 = *(const f32x4*)(gate + 4);
;         *(f32x4*)dst = a0 + g0 * v0; *(f32x4*)(dst + 4) = a1 + g1 * v1;
	v_pk_fma_f32 v[186:187], v[60:61], v[164:165], v[186:187]
	v_pk_fma_f32 v[188:189], v[62:63], v[166:167], v[188:189]
	v_pk_fma_f32 v[190:191], v[56:57], v[168:169], v[190:191]
	v_pk_fma_f32 v[192:193], v[58:59], v[170:171], v[192:193]
	v_pk_fma_f32 v[194:195], v[48:49], v[176:177], v[194:195]
	v_pk_fma_f32 v[196:197], v[50:51], v[178:179], v[196:197]
	v_pk_fma_f32 v[198:199], v[44:45], v[182:183], v[198:199]
	v_pk_fma_f32 v[200:201], v[46:47], v[184:185], v[200:201]
	v_pk_fma_f32 v[202:203], v[52:53], v[164:165], v[202:203]
	v_pk_fma_f32 v[204:205], v[54:55], v[166:167], v[204:205]
	v_pk_fma_f32 v[206:207], v[40:41], v[168:169], v[206:207]
	v_pk_fma_f32 v[208:209], v[42:43], v[170:171], v[208:209]
	v_pk_fma_f32 v[210:211], v[32:33], v[176:177], v[210:211]
	v_pk_fma_f32 v[212:213], v[34:35], v[178:179], v[212:213]
	v_pk_fma_f32 v[214:215], v[28:29], v[182:183], v[214:215]
	v_pk_fma_f32 v[216:217], v[30:31], v[184:185], v[216:217]
	global_store_dwordx4 v[218:219], v[186:189], off
	global_store_dwordx4 v[218:219], v[190:193], off offset:16
	global_store_dwordx4 v[218:219], v[194:197], off offset:512
	global_store_dwordx4 v[218:219], v[198:201], off offset:528
	global_store_dwordx4 v[220:221], v[202:205], off
	global_store_dwordx4 v[220:221], v[206:209], off offset:16
	global_store_dwordx4 v[220:221], v[210:213], off offset:512
	global_store_dwordx4 v[220:221], v[214:217], off offset:528
	s_nop 1
	v_add_u32_e32 v218, s21, v157
	v_add_u32_e32 v222, s19, v157
	v_ashrrev_i32_e32 v219, 31, v218
	v_ashrrev_i32_e32 v223, 31, v222
	v_lshlrev_b64 v[218:219], 12, v[218:219]
	v_lshlrev_b64 v[222:223], 12, v[222:223]
	v_lshl_add_u64 v[218:219], s[8:9], 0, v[218:219]
	v_lshl_add_u64 v[222:223], s[14:15], 0, v[222:223]
	v_cndmask_b32_e32 v219, v223, v219, vcc
	v_cndmask_b32_e32 v218, v222, v218, vcc
	v_lshl_add_u64 v[218:219], v[218:219], 0, v[150:151]
	v_add_u32_e32 v220, s21, v158
	v_add_u32_e32 v222, s19, v158
	v_ashrrev_i32_e32 v221, 31, v220
	v_ashrrev_i32_e32 v223, 31, v222
	v_lshlrev_b64 v[220:221], 12, v[220:221]
	v_lshlrev_b64 v[222:223], 12, v[222:223]
	v_lshl_add_u64 v[220:221], s[8:9], 0, v[220:221]
	v_lshl_add_u64 v[222:223], s[14:15], 0, v[222:223]
	v_cndmask_b32_e32 v221, v223, v221, vcc
	v_cndmask_b32_e32 v220, v222, v220, vcc
	v_lshl_add_u64 v[220:221], v[220:221], 0, v[150:151]
	global_load_dwordx4 v[186:189], v[218:219], off
	global_load_dwordx4 v[190:193], v[218:219], off offset:16
	global_load_dwordx4 v[194:197], v[218:219], off offset:512
	global_load_dwordx4 v[198:201], v[218:219], off offset:528
	global_load_dwordx4 v[202:205], v[220:221], off
	global_load_dwordx4 v[206:209], v[220:221], off offset:16
	global_load_dwordx4 v[210:213], v[220:221], off offset:512
	global_load_dwordx4 v[214:217], v[220:221], off offset:528
	s_waitcnt vmcnt(0)
	v_pk_fma_f32 v[186:187], v[36:37], v[164:165], v[186:187]
	v_pk_fma_f32 v[188:189], v[38:39], v[166:167], v[188:189]
	v_pk_fma_f32 v[190:191], v[24:25], v[168:169], v[190:191]
	v_pk_fma_f32 v[192:193], v[26:27], v[170:171], v[192:193]
	v_pk_fma_f32 v[194:195], v[16:17], v[176:177], v[194:195]
	v_pk_fma_f32 v[196:197], v[18:19], v[178:179], v[196:197]
	v_pk_fma_f32 v[198:199], v[12:13], v[182:183], v[198:199]
	v_pk_fma_f32 v[200:201], v[14:15], v[184:185], v[200:201]
	v_pk_fma_f32 v[202:203], v[20:21], v[164:165], v[202:203]
	v_pk_fma_f32 v[204:205], v[22:23], v[166:167], v[204:205]
	v_pk_fma_f32 v[206:207], v[8:9], v[168:169], v[206:207]
	v_pk_fma_f32 v[208:209], v[10:11], v[170:171], v[208:209]
	v_pk_fma_f32 v[210:211], v[4:5], v[176:177], v[210:211]
	v_pk_fma_f32 v[212:213], v[6:7], v[178:179], v[212:213]
	v_pk_fma_f32 v[214:215], v[0:1], v[182:183], v[214:215]
	v_pk_fma_f32 v[216:217], v[2:3], v[184:185], v[216:217]
	global_store_dwordx4 v[218:219], v[186:189], off
	global_store_dwordx4 v[218:219], v[190:193], off offset:16
	global_store_dwordx4 v[218:219], v[194:197], off offset:512
	global_store_dwordx4 v[218:219], v[198:201], off offset:528
	global_store_dwordx4 v[220:221], v[202:205], off
	global_store_dwordx4 v[220:221], v[206:209], off offset:16
	global_store_dwordx4 v[220:221], v[210:213], off offset:512
	global_store_dwordx4 v[220:221], v[214:217], off offset:528
	s_nop 1
	s_andn2_b64 vcc, exec, s[24:25]
	s_mov_b64 s[24:25], -1
	s_cbranch_vccnz .LBB0_1953
	s_andn2_b64 vcc, exec, s[6:7]
	s_cbranch_vccnz .LBB0_1952
	s_barrier
	s_branch .LBB0_1952

;     __device__ __forceinline__ void operator()(const f32x4 (&acc)[2][2][4][2], const Unit& u, int wr, int wc, int fr, int fq) const {
;     ...
;         for (int ai = 0; ai < 2; ++ai)
; #pragma unroll
;             for (int m = 0; m < 4; ++m)
; #pragma unroll
;                 for (int bj = 0; bj < 2; ++bj) f(u, ai * 128 + wr * 64 + m * 16 + fr, bj * 128 + wc * 32 + 8 * fq, acc[ai][bj][m][0], acc[ai][bj][m][1]);
;     __device__ __forceinline__ void operator()(const pg8::Unit& u, int rl, int cl, f32x4 v0, f32x4 v1) const {
;         const int b = u.pm / 17, j = u.pm - 17 * b, col = u.pn * 256 + cl;
;         const float* src; float* dst; const float* gate;
;         if (j == 0) { const size_t off = (size_t)(b * CTXL + rl) * D + col; src = co + off; dst = cn + off; gate = modl + 4 * 3072 + 2048 + col; }
;         else { const size_t off = (size_t)(b * SEQ + (j - 1) * 256 + rl) * D + col; src = xo + off; dst = xn + off; gate = modl + b * 3072 + 2048 + col; }
;         const f32x4 a0 = *(const f32x4*)src, a1 = *(const f32x4*)(src + 4), g0 = *(const f32x4*)gate, g1 = *(const f32x4*)(gate + 4);
;         *(f32x4*)dst = a0 + g0 * v0; *(f32x4*)(dst + 4) = a1 + g1 * v1;
;     }
.LBB0_2666:
	s_mul_hi_i32 s15, s24, 0x78787879
	s_lshr_b32 s17, s15, 31
	s_ashr_i32 s15, s15, 3
	s_add_i32 s17, s15, s17
	s_mul_i32 s15, s17, 0xffffffef
	s_add_i32 s24, s15, s24
	s_lshl_b32 s15, s17, 12
	s_lshl_b32 s36, s24, 8
	s_add_i32 s15, s15, s36
	s_mul_i32 s36, s17, 0xc00
	s_ashr_i32 s37, s36, 31
	s_addk_i32 s15, 0xff00
	s_lshl_b32 s17, s17, 8
	s_lshl_b64 s[36:37], s[36:37], 2
	s_add_u32 s36, s26, s36
	s_addc_u32 s37, s27, s37
	s_add_u32 s38, s36, 0x2f000
	s_addc_u32 s39, s37, 0
	v_add_u32_e32 v142, s15, v144
	v_add_u32_e32 v158, s17, v144
	s_cmp_eq_u32 s24, 0
	v_ashrrev_i32_e32 v143, 31, v142
	v_ashrrev_i32_e32 v159, 31, v158
	v_lshl_or_b32 v140, s59, 8, v153
	v_lshlrev_b64 v[158:159], 12, v[158:159]
	v_lshlrev_b64 v[142:143], 12, v[142:143]
	s_cselect_b64 vcc, -1, 0
	v_ashrrev_i32_e32 v141, 31, v140
	v_lshl_add_u64 v[158:159], s[8:9], 0, v[158:159]
	v_lshl_add_u64 v[142:143], s[0:1], 0, v[142:143]
	s_and_b64 s[36:37], vcc, exec
	v_cndmask_b32_e32 v159, v143, v159, vcc
	s_cselect_b32 s37, s54, s39
	s_cselect_b32 s36, s53, s38
	v_cndmask_b32_e32 v158, v142, v158, vcc
	v_lshlrev_b64 v[142:143], 2, v[140:141]
	v_lshl_add_u64 v[140:141], s[36:37], 0, v[142:143]
	v_lshl_add_u64 v[174:175], v[158:159], 0, v[142:143]
	global_load_dwordx4 v[158:161], v[140:141], off
	global_load_dwordx4 v[162:165], v[140:141], off offset:16
	global_load_dwordx4 v[170:173], v[140:141], off offset:512
	global_load_dwordx4 v[176:179], v[140:141], off offset:528
	v_add_u32_e32 v214, s17, v146
	v_add_u32_e32 v216, s15, v146
	v_ashrrev_i32_e32 v215, 31, v214
	v_ashrrev_i32_e32 v217, 31, v216
	v_lshlrev_b64 v[214:215], 12, v[214:215]
	v_lshlrev_b64 v[216:217], 12, v[216:217]
	v_lshl_add_u64 v[214:215], s[8:9], 0, v[214:215]
	v_lshl_add_u64 v[216:217], s[0:1], 0, v[216:217]
	v_cndmask_b32_e32 v215, v217, v215, vcc
	v_cndmask_b32_e32 v214, v216, v214, vcc
	v_lshl_add_u64 v[214:215], v[214:215], 0, v[142:143]
	global_load_dwordx4 v[180:183], v[174:175], off
	global_load_dwordx4 v[184:187], v[174:175], off offset:16
	global_load_dwordx4 v[188:191], v[174:175], off offset:512
	global_load_dwordx4 v[192:195], v[174:175], off offset:528
	global_load_dwordx4 v[196:199], v[214:215], off
	global_load_dwordx4 v[200:203], v[214:215], off offset:16
	global_load_dwordx4 v[204:207], v[214:215], off offset:512
	global_load_dwordx4 v[208:211], v[214:215], off offset:528
	s_waitcnt vmcnt(0)
	v_pk_fma_f32 v[180:181], v[124:125], v[158:159], v[180:181]
	v_pk_fma_f32 v[182:183], v[126:127], v[160:161], v[182:183]
	v_pk_fma_f32 v[184:185], v[120:121], v[162:163], v[184:185]
	v_pk_fma_f32 v[186:187], v[122:123], v[164:165], v[186:187]
	v_pk_fma_f32 v[188:189], v[112:113], v[170:171], v[188:189]
	v_pk_fma_f32 v[190:191], v[114:115], v[172:173], v[190:191]
	v_pk_fma_f32 v[192:193], v[108:109], v[176:177], v[192:193]
	v_pk_fma_f32 v[194:195], v[110:111], v[178:179], v[194:195]
	v_pk_fma_f32 v[196:197], v[116:117], v[158:159], v[196:197]
	v_pk_fma_f32 v[198:199], v[118:119], v[160:161], v[198:199]
	v_pk_fma_f32 v[200:201], v[104:105], v[162:163], v[200:201]
	v_pk_fma_f32 v[202:203], v[106:107], v[164:165], v[202:203]
	v_pk_fma_f32 v[204:205], v[96:97], v[170:171], v[204:205]
	v_pk_fma_f32 v[206:207], v[98:99], v[172:173], v[206:207]
	v_pk_fma_f32 v[208:209], v[92:93], v[176:177], v[208:209]
	v_pk_fma_f32 v[210:211], v[94:95], v[178:179], v[210:211]
	global_store_dwordx4 v[174:175], v[180:183], off
	global_store_dwordx4 v[174:175], v[184:187], off offset:16
	global_store_dwordx4 v[174:175], v[188:191], off offset:512
	global_store_dwordx4 v[174:175], v[192:195], off offset:528
	global_store_dwordx4 v[214:215], v[196:199], off
	global_store_dwordx4 v[214:215], v[200:203], off offset:16
	global_store_dwordx4 v[214:215], v[204:207], off offset:512
	global_store_dwordx4 v[214:215], v[208:211], off offset:528
	s_nop 1
	v_add_u32_e32 v212, s17, v147
	v_add_u32_e32 v216, s15, v147
	v_ashrrev_i32_e32 v213, 31, v212
	v_ashrrev_i32_e32 v217, 31, v216
	v_lshlrev_b64 v[212:213], 12, v[212:213]
	v_lshlrev_b64 v[216:217], 12, v[216:217]
	v_lshl_add_u64 v[212:213], s[8:9], 0, v[212:213]
	v_lshl_add_u64 v[216:217], s[0:1], 0, v[216:217]
	v_cndmask_b32_e32 v213, v217, v213, vcc
	v_cndmask_b32_e32 v212, v216, v212, vcc
	v_lshl_add_u64 v[212:213], v[212:213], 0, v[142:143]
	v_add_u32_e32 v214, s17, v148
	v_add_u32_e32 v216, s15, v148
	v_ashrrev_i32_e32 v215, 31, v214
	v_ashrrev_i32_e32 v217, 31, v216
	v_lshlrev_b64 v[214:215], 12, v[214:215]
	v_lshlrev_b64 v[216:217], 12, v[216:217]
	v_lshl_add_u64 v[214:215], s[8:9], 0, v[214:215]
	v_lshl_add_u64 v[216:217], s[0:1], 0, v[216:217]
	v_cndmask_b32_e32 v215, v217, v215, vcc
	v_cndmask_b32_e32 v214, v216, v214, vcc
	v_lshl_add_u64 v[214:215], v[214:215], 0, v[142:143]
	global_load_dwordx4 v[180:183], v[212:213], off
	global_load_dwordx4 v[184:187], v[212:213], off offset:16
	global_load_dwordx4 v[188:191], v[212:213], off offset:512
	global_load_dwordx4 v[192:195], v[212:213], off offset:528
	global_load_dwordx4 v[196:199], v[214:215], off
	global_load_dwordx4 v[200:203], v[214:215], off offset:16
	global_load_dwordx4 v[204:207], v[214:215], off offset:512
	global_load_dwordx4 v[208:211], v[214:215], off offset:528
	s_waitcnt vmcnt(0)
;     __device__ __forceinline__ void operator()(const pg8::Unit& u, int rl, int cl, f32x4 v0, f32x4 v1) const {
;         const int b = u.pm / 17, j = u.pm - 17 * b, col = u.pn * 256 + cl;
;         const float* src; float* dst; const float* gate;
;         if (j == 0) { const size_t off = (size_t)(b * CTXL + rl) * D + col; src = co + off; dst = cn + off; gate = modl + 4 * 3072 + 2048 + col; }
;         else { const size_t off = (size_t)(b * SEQ + (j - 1) * 256 + rl) * D + col; src = xo + off; dst = xn + off; gate = modl + b * 3072 + 2048 + col; }
;         const f32x4 a0 = *(const f32x4*)src, a1 = *(const f32x4*)(src + 4), g0 = *(const f32x4*)gate, g1 = *(const f32x4*)(gate + 4);
;         *(f32x4*)dst = a0 + g0 * v0; *(f32x4*)(dst + 4) = a1 + g1 * v1;
	v_pk_fma_f32 v[180:181], v[100:101], v[158:159], v[180:181]
	v_pk_fma_f32 v[182:183], v[102:103], v[160:161], v[182:183]
	v_pk_fma_f32 v[184:185], v[88:89], v[162:163], v[184:185]
	v_pk_fma_f32 v[186:187], v[90:91], v[164:165], v[186:187]
	v_pk_fma_f32 v[188:189], v[80:81], v[170:171], v[188:189]
	v_pk_fma_f32 v[190:191], v[82:83], v[172:173], v[190:191]
	v_pk_fma_f32 v[192:193], v[76:77], v[176:177], v[192:193]
	v_pk_fma_f32 v[194:195], v[78:79], v[178:179], v[194:195]
	v_pk_fma_f32 v[196:197], v[84:85], v[158:159], v[196:197]
	v_pk_fma_f32 v[198:199], v[86:87], v[160:161], v[198:199]
	v_pk_fma_f32 v[200:201], v[72:73], v[162:163], v[200:201]
	v_pk_fma_f32 v[202:203], v[74:75], v[164:165], v[202:203]
	v_pk_fma_f32 v[204:205], v[68:69], v[170:171], v[204:205]
	v_pk_fma_f32 v[206:207], v[70:71], v[172:173], v[206:207]
	v_pk_fma_f32 v[208:209], v[64:65], v[176:177], v[208:209]
	v_pk_fma_f32 v[210:211], v[66:67], v[178:179], v[210:211]
	global_store_dwordx4 v[212:213], v[180:183], off
	global_store_dwordx4 v[212:213], v[184:187], off offset:16
	global_store_dwordx4 v[212:213], v[188:191], off offset:512
	global_store_dwordx4 v[212:213], v[192:195], off offset:528
	global_store_dwordx4 v[214:215], v[196:199], off
	global_store_dwordx4 v[214:215], v[200:203], off offset:16
	global_store_dwordx4 v[214:215], v[204:207], off offset:512
	global_store_dwordx4 v[214:215], v[208:211], off offset:528
	s_nop 1
	v_add_u32_e32 v212, s17, v149
	v_add_u32_e32 v216, s15, v149
	v_ashrrev_i32_e32 v213, 31, v212
	v_ashrrev_i32_e32 v217, 31, v216
	v_lshlrev_b64 v[212:213], 12, v[212:213]
	v_lshlrev_b64 v[216:217], 12, v[216:217]
	v_lshl_add_u64 v[212:213], s[8:9], 0, v[212:213]
	v_lshl_add_u64 v[216:217], s[0:1], 0, v[216:217]
	v_cndmask_b32_e32 v213, v217, v213, vcc
	v_cndmask_b32_e32 v212, v216, v212, vcc
	v_lshl_add_u64 v[212:213], v[212:213], 0, v[142:143]
	v_add_u32_e32 v214, s17, v150
	v_add_u32_e32 v216, s15, v150
	v_ashrrev_i32_e32 v215, 31, v214
	v_ashrrev_i32_e32 v217, 31, v216
	v_lshlrev_b64 v[214:215], 12, v[214:215]
	v_lshlrev_b64 v[216:217], 12, v[216:217]
	v_lshl_add_u64 v[214:215], s[8:9], 0, v[214:215]
	v_lshl_add_u64 v[216:217], s[0:1], 0, v[216:217]
	v_cndmask_b32_e32 v215, v217, v215, vcc
	v_cndmask_b32_e32 v214, v216, v214, vcc
	v_lshl_add_u64 v[214:215], v[214:215], 0, v[142:143]
	global_load_dwordx4 v[180:183], v[212:213], off
	global_load_dwordx4 v[184:187], v[212:213], off offset:16
	global_load_dwordx4 v[188:191], v[212:213], off offset:512
	global_load_dwordx4 v[192:195], v[212:213], off offset:528
	global_load_dwordx4 v[196:199], v[214:215], off
	global_load_dwordx4 v[200:203], v[214:215], off offset:16
	global_load_dwordx4 v[204:207], v[214:215], off offset:512
	global_load_dwordx4 v[208:211], v[214:215], off offset:528
	s_waitcnt vmcnt(0)
; #define PG8_BAR __builtin_amdgcn_s_barrier()
; template <class Epi, class Sched, bool ALIGN_EPI = false, bool SP2 = false>
; __device__ __forceinline__ void gemm_phase(PG8_LAS unsigned char* lds, const Gemm g, const Sched& S, const Epi& E) {
;     ...
;         if constexpr (ALIGN_EPI) { if (wr == 0) PG8_BAR; }
;         if constexpr (!Epi::AFTER_DRAIN) { E(acc, cur, wr, wc, fr, fq); S.done(cur); }
;         if (!has_next) break;
; #pragma unroll
;         for (int a = 0; a < 2; ++a)
; #pragma unroll
;             for (int b = 0; b < 2; ++b)
; #pragma unroll
;                 for (int m = 0; m < 4; ++m)
; #pragma unroll
;                     for (int n = 0; n < 2; ++n) acc[a][b][m][n] = (f32x4){0.f, 0.f, 0.f, 0.f};
;         cur = nxt; cA = nA; cB = nB; ++ui;
;         if constexpr (ALIGN_EPI) { if (wr == 1) PG8_BAR; }
;     __device__ __forceinline__ void operator()(const pg8::Unit& u, int rl, int cl, f32x4 v0, f32x4 v1) const {
;         const int b = u.pm / 17, j = u.pm - 17 * b, col = u.pn * 256 + cl;
;         const float* src; float* dst; const float* gate;
;         if (j == 0) { const size_t off = (size_t)(b * CTXL + rl) * D + col; src = co + off; dst = cn + off; gate = modl + 4 * 3072 + 2048 + col; }
;         else { const size_t off = (size_t)(b * SEQ + (j - 1) * 256 + rl) * D + col; src = xo + off; dst = xn + off; gate = modl + b * 3072 + 2048 + col; }
;         const f32x4 a0 = *(const f32x4*)src, a1 = *(const f32x4*)(src + 4), g0 = *(const f32x4*)gate, g1 = *(const f32x4*)(gate + 4);
;         *(f32x4*)dst = a0 + g0 * v0; *(f32x4*)(dst + 4) = a1 + g1 * v1;
	v_pk_fma_f32 v[180:181], v[60:61], v[158:159], v[180:181]
	v_pk_fma_f32 v[182:183], v[62:63], v[160:161], v[182:183]
	v_pk_fma_f32 v[184:185], v[56:57], v[162:163], v[184:185]
	v_pk_fma_f32 v[186:187], v[58:59], v[164:165], v[186:187]
	v_pk_fma_f32 v[188:189], v[48:49], v[170:171], v[188:189]
	v_pk_fma_f32 v[190:191], v[50:51], v[172:173], v[190:191]
	v_pk_fma_f32 v[192:193], v[44:45], v[176:177], v[192:193]
	v_pk_fma_f32 v[194:195], v[46:47], v[178:179], v[194:195]
	v_pk_fma_f32 v[196:197], v[52:53], v[158:159], v[196:197]
	v_pk_fma_f32 v[198:199], v[54:55], v[160:161], v[198:199]
	v_pk_fma_f32 v[200:201], v[40:41], v[162:163], v[200:201]
	v_pk_fma_f32 v[202:203], v[42:43], v[164:165], v[202:203]
	v_pk_fma_f32 v[204:205], v[32:33], v[170:171], v[204:205]
	v_pk_fma_f32 v[206:207], v[34:35], v[172:173], v[206:207]
	v_pk_fma_f32 v[208:209], v[28:29], v[176:177], v[208:209]
	v_pk_fma_f32 v[210:211], v[30:31], v[178:179], v[210:211]
	global_store_dwordx4 v[212:213], v[180:183], off
	global_store_dwordx4 v[212:213], v[184:187], off offset:16
	global_store_dwordx4 v[212:213], v[188:191], off offset:512
	global_store_dwordx4 v[212:213], v[192:195], off offset:528
	global_store_dwordx4 v[214:215], v[196:199], off
	global_store_dwordx4 v[214:215], v[200:203], off offset:16
	global_store_dwordx4 v[214:215], v[204:207], off offset:512
	global_store_dwordx4 v[214:215], v[208:211], off offset:528
	s_nop 1
	v_add_u32_e32 v212, s17, v151
	v_add_u32_e32 v216, s15, v151
	v_ashrrev_i32_e32 v213, 31, v212
	v_ashrrev_i32_e32 v217, 31, v216
	v_lshlrev_b64 v[212:213], 12, v[212:213]
	v_lshlrev_b64 v[216:217], 12, v[216:217]
	v_lshl_add_u64 v[212:213], s[8:9], 0, v[212:213]
	v_lshl_add_u64 v[216:217], s[0:1], 0, v[216:217]
	v_cndmask_b32_e32 v213, v217, v213, vcc
	v_cndmask_b32_e32 v212, v216, v212, vcc
	v_lshl_add_u64 v[212:213], v[212:213], 0, v[142:143]
	v_add_u32_e32 v214, s17, v152
	v_add_u32_e32 v216, s15, v152
	v_ashrrev_i32_e32 v215, 31, v214
	v_ashrrev_i32_e32 v217, 31, v216
	v_lshlrev_b64 v[214:215], 12, v[214:215]
	v_lshlrev_b64 v[216:217], 12, v[216:217]
	v_lshl_add_u64 v[214:215], s[8:9], 0, v[214:215]
	v_lshl_add_u64 v[216:217], s[0:1], 0, v[216:217]
	v_cndmask_b32_e32 v215, v217, v215, vcc
	v_cndmask_b32_e32 v214, v216, v214, vcc
	v_lshl_add_u64 v[214:215], v[214:215], 0, v[142:143]
	global_load_dwordx4 v[180:183], v[212:213], off
	global_load_dwordx4 v[184:187], v[212:213], off offset:16
	global_load_dwordx4 v[188:191], v[212:213], off offset:512
	global_load_dwordx4 v[192:195], v[212:213], off offset:528
	global_load_dwordx4 v[196:199], v[214:215], off
	global_load_dwordx4 v[200:203], v[214:215], off offset:16
	global_load_dwordx4 v[204:207], v[214:215], off offset:512
	global_load_dwordx4 v[208:211], v[214:215], off offset:528
	s_waitcnt vmcnt(0)
	v_pk_fma_f32 v[180:181], v[36:37], v[158:159], v[180:181]
	v_pk_fma_f32 v[182:183], v[38:39], v[160:161], v[182:183]
	v_pk_fma_f32 v[184:185], v[24:25], v[162:163], v[184:185]
	v_pk_fma_f32 v[186:187], v[26:27], v[164:165], v[186:187]
	v_pk_fma_f32 v[188:189], v[16:17], v[170:171], v[188:189]
	v_pk_fma_f32 v[190:191], v[18:19], v[172:173], v[190:191]
	v_pk_fma_f32 v[192:193], v[12:13], v[176:177], v[192:193]
	v_pk_fma_f32 v[194:195], v[14:15], v[178:179], v[194:195]
	v_pk_fma_f32 v[196:197], v[20:21], v[158:159], v[196:197]
	v_pk_fma_f32 v[198:199], v[22:23], v[160:161], v[198:199]
	v_pk_fma_f32 v[200:201], v[8:9], v[162:163], v[200:201]
	v_pk_fma_f32 v[202:203], v[10:11], v[164:165], v[202:203]
	v_pk_fma_f32 v[204:205], v[4:5], v[170:171], v[204:205]
	v_pk_fma_f32 v[206:207], v[6:7], v[172:173], v[206:207]
	v_pk_fma_f32 v[208:209], v[0:1], v[176:177], v[208:209]
	v_pk_fma_f32 v[210:211], v[2:3], v[178:179], v[210:211]
	global_store_dwordx4 v[212:213], v[180:183], off
	global_store_dwordx4 v[212:213], v[184:187], off offset:16
	global_store_dwordx4 v[212:213], v[188:191], off offset:512
	global_store_dwordx4 v[212:213], v[192:195], off offset:528
	global_store_dwordx4 v[214:215], v[196:199], off
	global_store_dwordx4 v[214:215], v[200:203], off offset:16
	global_store_dwordx4 v[214:215], v[204:207], off offset:512
	global_store_dwordx4 v[214:215], v[208:211], off offset:528
	s_nop 1
	s_andn2_b64 vcc, exec, s[20:21]
	s_mov_b64 s[20:21], -1
	s_cbranch_vccnz .LBB0_2659
	s_andn2_b64 vcc, exec, s[6:7]
	s_cbranch_vccnz .LBB0_2658
	s_barrier
	s_branch .LBB0_2658
